# combo15 + same second-sub-tile K-read hoist in the dilated and stick-breaking loops
# baseline (speedup 1.0000x reference)
.LBB0_750:
	s_sub_i32 s6, s92, 32
	v_add_u32_e32 v32, s18, v97
	v_add_u32_e32 v99, v32, v118
	s_cmp_gt_i32 s6, s86
	v_add_u32_e32 v121, v32, v112
	v_add_u32_e32 v105, s89, v119
	ds_read_b128 v[218:221], v121 offset:4608
	ds_read_b128 v[222:225], v121 offset:4640
	ds_read_b128 v[226:229], v121 offset:4672
	ds_read_b128 v[230:233], v121 offset:4704
	s_cbranch_scc1 .LBB0_766
	ds_read_b128 v[32:35], v121
	ds_read_b128 v[36:39], v121 offset:32
	ds_read_b128 v[40:43], v121 offset:64
	ds_read_b128 v[44:47], v121 offset:96
	s_setprio 1
	s_waitcnt lgkmcnt(0)
	v_mfma_f32_32x32x16_bf16 v[48:63], v[32:35], v[64:67], 0
	v_mfma_f32_32x32x16_bf16 v[48:63], v[36:39], v[68:71], v[48:63]
	v_mfma_f32_32x32x16_bf16 v[48:63], v[40:43], v[72:75], v[48:63]
	v_mfma_f32_32x32x16_bf16 v[48:63], v[44:47], v[76:79], v[48:63]
	s_setprio 0
	s_sub_i32 s6, s89, 62
	v_subrev_u32_e32 v122, 31, v105
	s_cmpk_lt_i32 s6, 0x201
	s_mov_b64 s[18:19], -1
	s_cbranch_scc0 .LBB0_761
	s_cmpk_gt_i32 s6, 0x80
	s_cselect_b64 s[18:19], -1, 0
	s_cmpk_lt_i32 s89, 0x201
	s_cselect_b64 s[54:55], -1, 0
	s_and_b64 s[18:19], s[18:19], s[54:55]
	s_andn2_b64 vcc, exec, s[18:19]
	s_mov_b64 s[18:19], -1
	s_cbranch_vccz .LBB0_758
	s_cmp_gt_i32 s6, -1
	s_cselect_b64 s[18:19], -1, 0
	s_cmpk_lt_i32 s89, 0x81
	s_cselect_b64 s[54:55], -1, 0
	s_and_b64 s[54:55], s[18:19], s[54:55]
	s_mov_b64 s[18:19], -1
	s_and_b64 vcc, exec, s[54:55]
	s_cbranch_vccnz .LBB0_755
	s_movk_i32 s6, 0x81
	v_cmp_gt_i32_e32 vcc, s6, v122
	s_movk_i32 s6, 0x201
	v_and_b32_e32 v39, 15, v122
	v_cndmask_b32_e64 v32, 0, 1, vcc
	v_cmp_gt_i32_e32 vcc, s6, v122
	s_and_b64 s[18:19], s[42:43], vcc
	v_cndmask_b32_e64 v33, 0, 1, s[18:19]
	v_cmp_eq_u32_e32 vcc, 0, v39
	s_movk_i32 s6, 0x82
	s_nop 0
	v_addc_co_u32_e64 v32, s[54:55], v33, v32, vcc
	v_cmp_eq_u32_e64 s[54:55], 2, v32
	v_cmp_ne_u32_e64 s[56:57], 0, v32
	s_nop 0
	v_cndmask_b32_e64 v33, 0, 1.0, s[54:55]
	v_cmp_gt_u32_e64 s[54:55], 3, v32
	s_nop 1
	v_cndmask_b32_e64 v33, v214, v33, s[54:55]
	v_cmp_lt_i32_e64 s[54:55], -1, v122
	v_fmac_f32_e32 v33, 0x3e38aa3b, v48
	s_and_b64 s[54:55], s[54:55], s[56:57]
	v_cndmask_b32_e64 v32, v212, v33, s[54:55]
	v_cmp_gt_i32_e64 s[54:55], s6, v122
	s_movk_i32 s6, 0x202
	s_nop 0
	v_cndmask_b32_e64 v33, 0, 1, s[54:55]
	v_cmp_gt_i32_e64 s[54:55], s6, v122
	s_and_b64 s[18:19], s[44:45], s[54:55]
	v_cndmask_b32_e64 v34, 0, 1, s[18:19]
	v_cmp_eq_u32_e64 s[54:55], 1, v39
	s_movk_i32 s6, 0x83
	s_nop 0
	v_addc_co_u32_e64 v33, s[56:57], v34, v33, s[54:55]
	v_cmp_eq_u32_e64 s[56:57], 2, v33
	v_cmp_ne_u32_e64 s[58:59], 0, v33
	s_nop 0
	v_cndmask_b32_e64 v34, 0, 1.0, s[56:57]
	v_cmp_gt_u32_e64 s[56:57], 3, v33
	s_nop 1
	v_cndmask_b32_e64 v34, v214, v34, s[56:57]
	v_cmp_lt_i32_e64 s[56:57], 0, v122
	v_fmac_f32_e32 v34, 0x3e38aa3b, v49
	s_and_b64 s[56:57], s[56:57], s[58:59]
	v_cndmask_b32_e64 v33, v212, v34, s[56:57]
	v_cmp_gt_i32_e64 s[56:57], s6, v122
	s_movk_i32 s6, 0x203
	s_nop 0
	v_cndmask_b32_e64 v34, 0, 1, s[56:57]
	v_cmp_gt_i32_e64 s[56:57], s6, v122
	s_and_b64 s[18:19], s[46:47], s[56:57]
	v_cndmask_b32_e64 v35, 0, 1, s[18:19]
	v_cmp_eq_u32_e64 s[56:57], 2, v39
	s_movk_i32 s6, 0x84
	s_nop 0
	v_addc_co_u32_e64 v34, s[58:59], v35, v34, s[56:57]
	v_cmp_eq_u32_e64 s[58:59], 2, v34
	v_cmp_ne_u32_e64 s[60:61], 0, v34
	s_nop 0
	v_cndmask_b32_e64 v35, 0, 1.0, s[58:59]
	v_cmp_gt_u32_e64 s[58:59], 3, v34
	s_nop 1
	v_cndmask_b32_e64 v35, v214, v35, s[58:59]
	v_cmp_lt_i32_e64 s[58:59], 1, v122
	v_fmac_f32_e32 v35, 0x3e38aa3b, v50
	s_and_b64 s[58:59], s[58:59], s[60:61]
	v_cndmask_b32_e64 v34, v212, v35, s[58:59]
	v_cmp_gt_i32_e64 s[58:59], s6, v122
	s_movk_i32 s6, 0x204
	s_nop 0
	v_cndmask_b32_e64 v35, 0, 1, s[58:59]
	v_cmp_gt_i32_e64 s[58:59], s6, v122
	s_and_b64 s[18:19], s[48:49], s[58:59]
	v_cndmask_b32_e64 v36, 0, 1, s[18:19]
	v_cmp_eq_u32_e64 s[58:59], 3, v39
	s_movk_i32 s6, 0x89
	s_nop 0
	v_addc_co_u32_e64 v35, s[60:61], v36, v35, s[58:59]
	v_cmp_eq_u32_e64 s[60:61], 2, v35
	v_cmp_ne_u32_e64 s[62:63], 0, v35
	s_nop 0
	v_cndmask_b32_e64 v36, 0, 1.0, s[60:61]
	v_cmp_gt_u32_e64 s[60:61], 3, v35
	s_nop 1
	v_cndmask_b32_e64 v36, v214, v36, s[60:61]
	v_cmp_lt_i32_e64 s[60:61], 2, v122
	v_fmac_f32_e32 v36, 0x3e38aa3b, v51
	s_and_b64 s[60:61], s[60:61], s[62:63]
	v_cndmask_b32_e64 v35, v212, v36, s[60:61]
	v_cmp_gt_i32_e64 s[60:61], s6, v122
	s_movk_i32 s6, 0x209
	s_nop 0
	v_cndmask_b32_e64 v36, 0, 1, s[60:61]
	v_cmp_gt_i32_e64 s[60:61], s6, v122
	s_and_b64 s[18:19], s[42:43], s[60:61]
	v_cndmask_b32_e64 v37, 0, 1, s[18:19]
	v_cmp_eq_u32_e64 s[60:61], 8, v39
	s_movk_i32 s6, 0x8a
	s_nop 0
	v_addc_co_u32_e64 v36, s[62:63], v37, v36, s[60:61]
	v_cmp_eq_u32_e64 s[62:63], 2, v36
	v_cmp_ne_u32_e64 s[64:65], 0, v36
	s_nop 0
	v_cndmask_b32_e64 v37, 0, 1.0, s[62:63]
	v_cmp_gt_u32_e64 s[62:63], 3, v36
	s_nop 1
	v_cndmask_b32_e64 v37, v214, v37, s[62:63]
	v_cmp_lt_i32_e64 s[62:63], 7, v122
	v_fmac_f32_e32 v37, 0x3e38aa3b, v52
	s_and_b64 s[62:63], s[62:63], s[64:65]
	v_cndmask_b32_e64 v36, v212, v37, s[62:63]
	v_cmp_gt_i32_e64 s[62:63], s6, v122
	s_movk_i32 s6, 0x20a
	s_nop 0
	v_cndmask_b32_e64 v37, 0, 1, s[62:63]
	v_cmp_gt_i32_e64 s[62:63], s6, v122
	s_and_b64 s[18:19], s[44:45], s[62:63]
	v_cndmask_b32_e64 v38, 0, 1, s[18:19]
	v_cmp_eq_u32_e64 s[62:63], 9, v39
	s_movk_i32 s6, 0x8b
	s_nop 0
	v_addc_co_u32_e64 v37, s[64:65], v38, v37, s[62:63]
	v_cmp_eq_u32_e64 s[64:65], 2, v37
	v_cmp_ne_u32_e64 s[66:67], 0, v37
	s_nop 0
	v_cndmask_b32_e64 v38, 0, 1.0, s[64:65]
	v_cmp_gt_u32_e64 s[64:65], 3, v37
	s_nop 1
	v_cndmask_b32_e64 v38, v214, v38, s[64:65]
	v_cmp_lt_i32_e64 s[64:65], 8, v122
	v_fmac_f32_e32 v38, 0x3e38aa3b, v53
	s_and_b64 s[64:65], s[64:65], s[66:67]
	v_cndmask_b32_e64 v37, v212, v38, s[64:65]
	v_cmp_gt_i32_e64 s[64:65], s6, v122
	s_movk_i32 s6, 0x20b
	s_nop 0
	v_cndmask_b32_e64 v38, 0, 1, s[64:65]
	v_cmp_gt_i32_e64 s[64:65], s6, v122
	s_and_b64 s[18:19], s[46:47], s[64:65]
	v_cndmask_b32_e64 v40, 0, 1, s[18:19]
	v_cmp_eq_u32_e64 s[64:65], 10, v39
	s_movk_i32 s6, 0x8c
	s_nop 0
	v_addc_co_u32_e64 v38, s[66:67], v40, v38, s[64:65]
	v_cmp_eq_u32_e64 s[66:67], 2, v38
	v_cmp_ne_u32_e64 s[68:69], 0, v38
	s_nop 0
	v_cndmask_b32_e64 v40, 0, 1.0, s[66:67]
	v_cmp_gt_u32_e64 s[66:67], 3, v38
	s_nop 1
	v_cndmask_b32_e64 v40, v214, v40, s[66:67]
	v_cmp_lt_i32_e64 s[66:67], 9, v122
	v_fmac_f32_e32 v40, 0x3e38aa3b, v54
	s_and_b64 s[66:67], s[66:67], s[68:69]
	v_cndmask_b32_e64 v38, v212, v40, s[66:67]
	v_cmp_gt_i32_e64 s[66:67], s6, v122
	s_movk_i32 s6, 0x20c
	s_nop 0
	v_cndmask_b32_e64 v40, 0, 1, s[66:67]
	v_cmp_gt_i32_e64 s[66:67], s6, v122
	s_and_b64 s[18:19], s[48:49], s[66:67]
	v_cndmask_b32_e64 v41, 0, 1, s[18:19]
	v_cmp_eq_u32_e64 s[66:67], 11, v39
	s_movk_i32 s6, 0x91
	s_nop 0
	v_addc_co_u32_e64 v39, s[68:69], v41, v40, s[66:67]
	v_cmp_eq_u32_e64 s[68:69], 2, v39
	v_cmp_ne_u32_e64 s[70:71], 0, v39
	s_nop 0
	v_cndmask_b32_e64 v40, 0, 1.0, s[68:69]
	v_cmp_gt_u32_e64 s[68:69], 3, v39
	s_nop 1
	v_cndmask_b32_e64 v40, v214, v40, s[68:69]
	v_cmp_lt_i32_e64 s[68:69], 10, v122
	v_fmac_f32_e32 v40, 0x3e38aa3b, v55
	s_and_b64 s[68:69], s[68:69], s[70:71]
	v_cndmask_b32_e64 v39, v212, v40, s[68:69]
	v_cmp_gt_i32_e64 s[68:69], s6, v122
	s_movk_i32 s6, 0x211
	s_nop 0
	v_cndmask_b32_e64 v40, 0, 1, s[68:69]
	v_cmp_gt_i32_e64 s[68:69], s6, v122
	s_and_b64 s[18:19], s[42:43], s[68:69]
	v_cndmask_b32_e64 v41, 0, 1, s[18:19]
	v_addc_co_u32_e32 v40, vcc, v41, v40, vcc
	v_cmp_eq_u32_e32 vcc, 2, v40
	v_cmp_ne_u32_e64 s[68:69], 0, v40
	s_movk_i32 s6, 0x92
	v_cndmask_b32_e64 v41, 0, 1.0, vcc
	v_cmp_gt_u32_e32 vcc, 3, v40
	s_nop 1
	v_cndmask_b32_e32 v41, v214, v41, vcc
	v_cmp_lt_i32_e32 vcc, 15, v122
	v_fmac_f32_e32 v41, 0x3e38aa3b, v56
	s_and_b64 vcc, vcc, s[68:69]
	v_cndmask_b32_e32 v40, v212, v41, vcc
	v_cmp_gt_i32_e32 vcc, s6, v122
	s_movk_i32 s6, 0x212
	s_nop 0
	v_cndmask_b32_e64 v41, 0, 1, vcc
	v_cmp_gt_i32_e32 vcc, s6, v122
	s_and_b64 s[18:19], s[44:45], vcc
	v_cndmask_b32_e64 v42, 0, 1, s[18:19]
	v_addc_co_u32_e64 v41, vcc, v42, v41, s[54:55]
	v_cmp_eq_u32_e32 vcc, 2, v41
	v_cmp_ne_u32_e64 s[54:55], 0, v41
	s_movk_i32 s6, 0x93
	v_cndmask_b32_e64 v42, 0, 1.0, vcc
	v_cmp_gt_u32_e32 vcc, 3, v41
	s_nop 1
	v_cndmask_b32_e32 v42, v214, v42, vcc
	v_cmp_lt_i32_e32 vcc, 16, v122
	v_fmac_f32_e32 v42, 0x3e38aa3b, v57
	s_and_b64 vcc, vcc, s[54:55]
	v_cndmask_b32_e32 v41, v212, v42, vcc
	v_cmp_gt_i32_e32 vcc, s6, v122
	s_movk_i32 s6, 0x213
	s_nop 0
	v_cndmask_b32_e64 v42, 0, 1, vcc
	v_cmp_gt_i32_e32 vcc, s6, v122
	s_and_b64 s[18:19], s[46:47], vcc
	v_cndmask_b32_e64 v43, 0, 1, s[18:19]
	v_addc_co_u32_e64 v42, vcc, v43, v42, s[56:57]
	v_cmp_eq_u32_e32 vcc, 2, v42
	v_cmp_ne_u32_e64 s[54:55], 0, v42
	s_movk_i32 s6, 0x94
	v_cndmask_b32_e64 v43, 0, 1.0, vcc
	v_cmp_gt_u32_e32 vcc, 3, v42
	s_nop 1
	v_cndmask_b32_e32 v43, v214, v43, vcc
	v_cmp_lt_i32_e32 vcc, 17, v122
	v_fmac_f32_e32 v43, 0x3e38aa3b, v58
	s_and_b64 vcc, vcc, s[54:55]
	v_cndmask_b32_e32 v42, v212, v43, vcc
	v_cmp_gt_i32_e32 vcc, s6, v122
	s_movk_i32 s6, 0x214
	s_nop 0
	v_cndmask_b32_e64 v43, 0, 1, vcc
	v_cmp_gt_i32_e32 vcc, s6, v122
	s_and_b64 s[18:19], s[48:49], vcc
	v_cndmask_b32_e64 v44, 0, 1, s[18:19]
	v_addc_co_u32_e64 v43, vcc, v44, v43, s[58:59]
	v_cmp_eq_u32_e32 vcc, 2, v43
	v_cmp_ne_u32_e64 s[54:55], 0, v43
	s_movk_i32 s6, 0x99
	v_cndmask_b32_e64 v44, 0, 1.0, vcc
	v_cmp_gt_u32_e32 vcc, 3, v43
	s_nop 1
	v_cndmask_b32_e32 v44, v214, v44, vcc
	v_cmp_lt_i32_e32 vcc, 18, v122
	v_fmac_f32_e32 v44, 0x3e38aa3b, v59
	s_and_b64 vcc, vcc, s[54:55]
	v_cndmask_b32_e32 v43, v212, v44, vcc
	v_cmp_gt_i32_e32 vcc, s6, v122
	s_movk_i32 s6, 0x219
	s_nop 0
	v_cndmask_b32_e64 v44, 0, 1, vcc
	v_cmp_gt_i32_e32 vcc, s6, v122
	s_and_b64 s[18:19], s[42:43], vcc
	v_cndmask_b32_e64 v45, 0, 1, s[18:19]
	v_addc_co_u32_e64 v44, vcc, v45, v44, s[60:61]
	v_cmp_eq_u32_e32 vcc, 2, v44
	v_cmp_ne_u32_e64 s[54:55], 0, v44
	s_movk_i32 s6, 0x9a
	v_cndmask_b32_e64 v45, 0, 1.0, vcc
	v_cmp_gt_u32_e32 vcc, 3, v44
	s_nop 1
	v_cndmask_b32_e32 v45, v214, v45, vcc
	v_cmp_lt_i32_e32 vcc, 23, v122
	v_fmac_f32_e32 v45, 0x3e38aa3b, v60
	s_and_b64 vcc, vcc, s[54:55]
	v_cndmask_b32_e32 v44, v212, v45, vcc
	v_cmp_gt_i32_e32 vcc, s6, v122
	s_movk_i32 s6, 0x21a
	s_nop 0
	v_cndmask_b32_e64 v45, 0, 1, vcc
	v_cmp_gt_i32_e32 vcc, s6, v122
	s_and_b64 s[18:19], s[44:45], vcc
	v_cndmask_b32_e64 v46, 0, 1, s[18:19]
	v_addc_co_u32_e64 v45, vcc, v46, v45, s[62:63]
	v_cmp_eq_u32_e32 vcc, 2, v45
	v_cmp_ne_u32_e64 s[54:55], 0, v45
	s_movk_i32 s6, 0x9b
	v_cndmask_b32_e64 v46, 0, 1.0, vcc
	v_cmp_gt_u32_e32 vcc, 3, v45
	s_nop 1
	v_cndmask_b32_e32 v46, v214, v46, vcc
	v_cmp_lt_i32_e32 vcc, 24, v122
	v_fmac_f32_e32 v46, 0x3e38aa3b, v61
	s_and_b64 vcc, vcc, s[54:55]
	v_cndmask_b32_e32 v45, v212, v46, vcc
	v_cmp_gt_i32_e32 vcc, s6, v122
	s_movk_i32 s6, 0x21b
	s_nop 0
	v_cndmask_b32_e64 v46, 0, 1, vcc
	v_cmp_gt_i32_e32 vcc, s6, v122
	s_and_b64 s[18:19], s[46:47], vcc
	v_cndmask_b32_e64 v47, 0, 1, s[18:19]
	v_addc_co_u32_e64 v46, vcc, v47, v46, s[64:65]
	v_cmp_eq_u32_e32 vcc, 2, v46
	v_cmp_ne_u32_e64 s[54:55], 0, v46
	s_movk_i32 s6, 0x9c
	v_cndmask_b32_e64 v47, 0, 1.0, vcc
	v_cmp_gt_u32_e32 vcc, 3, v46
	s_nop 1
	v_cndmask_b32_e32 v47, v214, v47, vcc
	v_cmp_lt_i32_e32 vcc, 25, v122
	v_fmac_f32_e32 v47, 0x3e38aa3b, v62
	s_and_b64 vcc, vcc, s[54:55]
	v_cndmask_b32_e32 v46, v212, v47, vcc
	v_cmp_gt_i32_e32 vcc, s6, v122
	s_movk_i32 s6, 0x21c
	s_nop 0
	v_cndmask_b32_e64 v47, 0, 1, vcc
	v_cmp_gt_i32_e32 vcc, s6, v122
	s_and_b64 s[18:19], s[48:49], vcc
	v_cndmask_b32_e64 v123, 0, 1, s[18:19]
	v_addc_co_u32_e64 v47, vcc, v123, v47, s[66:67]
	v_cmp_eq_u32_e32 vcc, 2, v47
	v_cmp_ne_u32_e64 s[54:55], 0, v47
	s_mov_b64 s[18:19], 0
	v_cndmask_b32_e64 v123, 0, 1.0, vcc
	v_cmp_gt_u32_e32 vcc, 3, v47
	s_nop 1
	v_cndmask_b32_e32 v123, v214, v123, vcc
	v_cmp_lt_i32_e32 vcc, 26, v122
	v_fmac_f32_e32 v123, 0x3e38aa3b, v63
	s_and_b64 vcc, vcc, s[54:55]
	v_cndmask_b32_e32 v47, v212, v123, vcc

.LBB0_767:
	s_setprio 1
	s_waitcnt lgkmcnt(0)
	v_mfma_f32_32x32x16_bf16 v[48:63], v[218:221], v[64:67], 0
	v_mfma_f32_32x32x16_bf16 v[48:63], v[222:225], v[68:71], v[48:63]
	v_mfma_f32_32x32x16_bf16 v[48:63], v[226:229], v[72:75], v[48:63]
	v_mfma_f32_32x32x16_bf16 v[48:63], v[230:233], v[76:79], v[48:63]
	s_setprio 0
	s_add_i32 s6, s89, 0xffffffa2
	v_subrev_u32_e32 v120, 63, v105
	s_cmpk_gt_i32 s6, 0x200
	s_mov_b64 s[18:19], -1
	s_cbranch_scc1 .LBB0_777
	s_sub_i32 s33, s89, 32
	s_cmpk_gt_i32 s6, 0x80
	s_cselect_b64 s[18:19], -1, 0
	s_cmpk_lt_i32 s33, 0x201
	s_cselect_b64 s[54:55], -1, 0
	s_and_b64 s[54:55], s[18:19], s[54:55]
	s_mov_b64 s[18:19], -1
	s_and_b64 vcc, exec, s[54:55]
	s_cbranch_vccnz .LBB0_774
	s_cmp_gt_i32 s6, -1
	s_cselect_b64 s[18:19], -1, 0
	s_cmpk_lt_i32 s33, 0x81
	s_cselect_b64 s[54:55], -1, 0
	s_and_b64 s[54:55], s[18:19], s[54:55]
	s_mov_b64 s[18:19], -1
	s_and_b64 vcc, exec, s[54:55]
	s_cbranch_vccnz .LBB0_771
	s_movk_i32 s6, 0x81
	v_cmp_gt_i32_e32 vcc, s6, v120
	s_movk_i32 s6, 0x201
	v_and_b32_e32 v39, 15, v120
	v_cndmask_b32_e64 v32, 0, 1, vcc
	v_cmp_gt_i32_e32 vcc, s6, v120
	s_and_b64 s[18:19], s[42:43], vcc
	v_cndmask_b32_e64 v33, 0, 1, s[18:19]
	v_cmp_eq_u32_e32 vcc, 0, v39
	s_movk_i32 s6, 0x82
	s_nop 0
	v_addc_co_u32_e64 v32, s[54:55], v33, v32, vcc
	v_cmp_eq_u32_e64 s[54:55], 2, v32
	v_cmp_ne_u32_e64 s[56:57], 0, v32
	s_nop 0
	v_cndmask_b32_e64 v33, 0, 1.0, s[54:55]
	v_cmp_gt_u32_e64 s[54:55], 3, v32
	s_nop 1
	v_cndmask_b32_e64 v33, v214, v33, s[54:55]
	v_cmp_lt_i32_e64 s[54:55], -1, v120
	v_fmac_f32_e32 v33, 0x3e38aa3b, v48
	s_and_b64 s[54:55], s[54:55], s[56:57]
	v_cndmask_b32_e64 v32, v212, v33, s[54:55]
	v_cmp_gt_i32_e64 s[54:55], s6, v120
	s_movk_i32 s6, 0x202
	s_nop 0
	v_cndmask_b32_e64 v33, 0, 1, s[54:55]
	v_cmp_gt_i32_e64 s[54:55], s6, v120
	s_and_b64 s[18:19], s[44:45], s[54:55]
	v_cndmask_b32_e64 v34, 0, 1, s[18:19]
	v_cmp_eq_u32_e64 s[54:55], 1, v39
	s_movk_i32 s6, 0x83
	s_nop 0
	v_addc_co_u32_e64 v33, s[56:57], v34, v33, s[54:55]
	v_cmp_eq_u32_e64 s[56:57], 2, v33
	v_cmp_ne_u32_e64 s[58:59], 0, v33
	s_nop 0
	v_cndmask_b32_e64 v34, 0, 1.0, s[56:57]
	v_cmp_gt_u32_e64 s[56:57], 3, v33
	s_nop 1
	v_cndmask_b32_e64 v34, v214, v34, s[56:57]
	v_cmp_lt_i32_e64 s[56:57], 0, v120
	v_fmac_f32_e32 v34, 0x3e38aa3b, v49
	s_and_b64 s[56:57], s[56:57], s[58:59]
	v_cndmask_b32_e64 v33, v212, v34, s[56:57]
	v_cmp_gt_i32_e64 s[56:57], s6, v120
	s_movk_i32 s6, 0x203
	s_nop 0
	v_cndmask_b32_e64 v34, 0, 1, s[56:57]
	v_cmp_gt_i32_e64 s[56:57], s6, v120
	s_and_b64 s[18:19], s[46:47], s[56:57]
	v_cndmask_b32_e64 v35, 0, 1, s[18:19]
	v_cmp_eq_u32_e64 s[56:57], 2, v39
	s_movk_i32 s6, 0x84
	s_nop 0
	v_addc_co_u32_e64 v34, s[58:59], v35, v34, s[56:57]
	v_cmp_eq_u32_e64 s[58:59], 2, v34
	v_cmp_ne_u32_e64 s[60:61], 0, v34
	s_nop 0
	v_cndmask_b32_e64 v35, 0, 1.0, s[58:59]
	v_cmp_gt_u32_e64 s[58:59], 3, v34
	s_nop 1
	v_cndmask_b32_e64 v35, v214, v35, s[58:59]
	v_cmp_lt_i32_e64 s[58:59], 1, v120
	v_fmac_f32_e32 v35, 0x3e38aa3b, v50
	s_and_b64 s[58:59], s[58:59], s[60:61]
	v_cndmask_b32_e64 v34, v212, v35, s[58:59]
	v_cmp_gt_i32_e64 s[58:59], s6, v120
	s_movk_i32 s6, 0x204
	s_nop 0
	v_cndmask_b32_e64 v35, 0, 1, s[58:59]
	v_cmp_gt_i32_e64 s[58:59], s6, v120
	s_and_b64 s[18:19], s[48:49], s[58:59]
	v_cndmask_b32_e64 v36, 0, 1, s[18:19]
	v_cmp_eq_u32_e64 s[58:59], 3, v39
	s_movk_i32 s6, 0x89
	s_nop 0
	v_addc_co_u32_e64 v35, s[60:61], v36, v35, s[58:59]
	v_cmp_eq_u32_e64 s[60:61], 2, v35
	v_cmp_ne_u32_e64 s[62:63], 0, v35
	s_nop 0
	v_cndmask_b32_e64 v36, 0, 1.0, s[60:61]
	v_cmp_gt_u32_e64 s[60:61], 3, v35
	s_nop 1
	v_cndmask_b32_e64 v36, v214, v36, s[60:61]
	v_cmp_lt_i32_e64 s[60:61], 2, v120
	v_fmac_f32_e32 v36, 0x3e38aa3b, v51
	s_and_b64 s[60:61], s[60:61], s[62:63]
	v_cndmask_b32_e64 v35, v212, v36, s[60:61]
	v_cmp_gt_i32_e64 s[60:61], s6, v120
	s_movk_i32 s6, 0x209
	s_nop 0
	v_cndmask_b32_e64 v36, 0, 1, s[60:61]
	v_cmp_gt_i32_e64 s[60:61], s6, v120
	s_and_b64 s[18:19], s[42:43], s[60:61]
	v_cndmask_b32_e64 v37, 0, 1, s[18:19]
	v_cmp_eq_u32_e64 s[60:61], 8, v39
	s_movk_i32 s6, 0x8a
	s_nop 0
	v_addc_co_u32_e64 v36, s[62:63], v37, v36, s[60:61]
	v_cmp_eq_u32_e64 s[62:63], 2, v36
	v_cmp_ne_u32_e64 s[64:65], 0, v36
	s_nop 0
	v_cndmask_b32_e64 v37, 0, 1.0, s[62:63]
	v_cmp_gt_u32_e64 s[62:63], 3, v36
	s_nop 1
	v_cndmask_b32_e64 v37, v214, v37, s[62:63]
	v_cmp_lt_i32_e64 s[62:63], 7, v120
	v_fmac_f32_e32 v37, 0x3e38aa3b, v52
	s_and_b64 s[62:63], s[62:63], s[64:65]
	v_cndmask_b32_e64 v36, v212, v37, s[62:63]
	v_cmp_gt_i32_e64 s[62:63], s6, v120
	s_movk_i32 s6, 0x20a
	s_nop 0
	v_cndmask_b32_e64 v37, 0, 1, s[62:63]
	v_cmp_gt_i32_e64 s[62:63], s6, v120
	s_and_b64 s[18:19], s[44:45], s[62:63]
	v_cndmask_b32_e64 v38, 0, 1, s[18:19]
	v_cmp_eq_u32_e64 s[62:63], 9, v39
	s_movk_i32 s6, 0x8b
	s_nop 0
	v_addc_co_u32_e64 v37, s[64:65], v38, v37, s[62:63]
	v_cmp_eq_u32_e64 s[64:65], 2, v37
	v_cmp_ne_u32_e64 s[66:67], 0, v37
	s_nop 0
	v_cndmask_b32_e64 v38, 0, 1.0, s[64:65]
	v_cmp_gt_u32_e64 s[64:65], 3, v37
	s_nop 1
	v_cndmask_b32_e64 v38, v214, v38, s[64:65]
	v_cmp_lt_i32_e64 s[64:65], 8, v120
	v_fmac_f32_e32 v38, 0x3e38aa3b, v53
	s_and_b64 s[64:65], s[64:65], s[66:67]
	v_cndmask_b32_e64 v37, v212, v38, s[64:65]
	v_cmp_gt_i32_e64 s[64:65], s6, v120
	s_movk_i32 s6, 0x20b
	s_nop 0
	v_cndmask_b32_e64 v38, 0, 1, s[64:65]
	v_cmp_gt_i32_e64 s[64:65], s6, v120
	s_and_b64 s[18:19], s[46:47], s[64:65]
	v_cndmask_b32_e64 v40, 0, 1, s[18:19]
	v_cmp_eq_u32_e64 s[64:65], 10, v39
	s_movk_i32 s6, 0x8c
	s_nop 0
	v_addc_co_u32_e64 v38, s[66:67], v40, v38, s[64:65]
	v_cmp_eq_u32_e64 s[66:67], 2, v38
	v_cmp_ne_u32_e64 s[68:69], 0, v38
	s_nop 0
	v_cndmask_b32_e64 v40, 0, 1.0, s[66:67]
	v_cmp_gt_u32_e64 s[66:67], 3, v38
	s_nop 1
	v_cndmask_b32_e64 v40, v214, v40, s[66:67]
	v_cmp_lt_i32_e64 s[66:67], 9, v120
	v_fmac_f32_e32 v40, 0x3e38aa3b, v54
	s_and_b64 s[66:67], s[66:67], s[68:69]
	v_cndmask_b32_e64 v38, v212, v40, s[66:67]
	v_cmp_gt_i32_e64 s[66:67], s6, v120
	s_movk_i32 s6, 0x20c
	s_nop 0
	v_cndmask_b32_e64 v40, 0, 1, s[66:67]
	v_cmp_gt_i32_e64 s[66:67], s6, v120
	s_and_b64 s[18:19], s[48:49], s[66:67]
	v_cndmask_b32_e64 v41, 0, 1, s[18:19]
	v_cmp_eq_u32_e64 s[66:67], 11, v39
	s_movk_i32 s6, 0x91
	s_nop 0
	v_addc_co_u32_e64 v39, s[68:69], v41, v40, s[66:67]
	v_cmp_eq_u32_e64 s[68:69], 2, v39
	v_cmp_ne_u32_e64 s[70:71], 0, v39
	s_nop 0
	v_cndmask_b32_e64 v40, 0, 1.0, s[68:69]
	v_cmp_gt_u32_e64 s[68:69], 3, v39
	s_nop 1
	v_cndmask_b32_e64 v40, v214, v40, s[68:69]
	v_cmp_lt_i32_e64 s[68:69], 10, v120
	v_fmac_f32_e32 v40, 0x3e38aa3b, v55
	s_and_b64 s[68:69], s[68:69], s[70:71]
	v_cndmask_b32_e64 v39, v212, v40, s[68:69]
	v_cmp_gt_i32_e64 s[68:69], s6, v120
	s_movk_i32 s6, 0x211
	s_nop 0
	v_cndmask_b32_e64 v40, 0, 1, s[68:69]
	v_cmp_gt_i32_e64 s[68:69], s6, v120
	s_and_b64 s[18:19], s[42:43], s[68:69]
	v_cndmask_b32_e64 v41, 0, 1, s[18:19]
	v_addc_co_u32_e32 v40, vcc, v41, v40, vcc
	v_cmp_eq_u32_e32 vcc, 2, v40
	v_cmp_ne_u32_e64 s[68:69], 0, v40
	s_movk_i32 s6, 0x92
	v_cndmask_b32_e64 v41, 0, 1.0, vcc
	v_cmp_gt_u32_e32 vcc, 3, v40
	s_nop 1
	v_cndmask_b32_e32 v41, v214, v41, vcc
	v_cmp_lt_i32_e32 vcc, 15, v120
	v_fmac_f32_e32 v41, 0x3e38aa3b, v56
	s_and_b64 vcc, vcc, s[68:69]
	v_cndmask_b32_e32 v40, v212, v41, vcc
	v_cmp_gt_i32_e32 vcc, s6, v120
	s_movk_i32 s6, 0x212
	s_nop 0
	v_cndmask_b32_e64 v41, 0, 1, vcc
	v_cmp_gt_i32_e32 vcc, s6, v120
	s_and_b64 s[18:19], s[44:45], vcc
	v_cndmask_b32_e64 v42, 0, 1, s[18:19]
	v_addc_co_u32_e64 v41, vcc, v42, v41, s[54:55]
	v_cmp_eq_u32_e32 vcc, 2, v41
	v_cmp_ne_u32_e64 s[54:55], 0, v41
	s_movk_i32 s6, 0x93
	v_cndmask_b32_e64 v42, 0, 1.0, vcc
	v_cmp_gt_u32_e32 vcc, 3, v41
	s_nop 1
	v_cndmask_b32_e32 v42, v214, v42, vcc
	v_cmp_lt_i32_e32 vcc, 16, v120
	v_fmac_f32_e32 v42, 0x3e38aa3b, v57
	s_and_b64 vcc, vcc, s[54:55]
	v_cndmask_b32_e32 v41, v212, v42, vcc
	v_cmp_gt_i32_e32 vcc, s6, v120
	s_movk_i32 s6, 0x213
	s_nop 0
	v_cndmask_b32_e64 v42, 0, 1, vcc
	v_cmp_gt_i32_e32 vcc, s6, v120
	s_and_b64 s[18:19], s[46:47], vcc
	v_cndmask_b32_e64 v43, 0, 1, s[18:19]
	v_addc_co_u32_e64 v42, vcc, v43, v42, s[56:57]
	v_cmp_eq_u32_e32 vcc, 2, v42
	v_cmp_ne_u32_e64 s[54:55], 0, v42
	s_movk_i32 s6, 0x94
	v_cndmask_b32_e64 v43, 0, 1.0, vcc
	v_cmp_gt_u32_e32 vcc, 3, v42
	s_nop 1
	v_cndmask_b32_e32 v43, v214, v43, vcc
	v_cmp_lt_i32_e32 vcc, 17, v120
	v_fmac_f32_e32 v43, 0x3e38aa3b, v58
	s_and_b64 vcc, vcc, s[54:55]
	v_cndmask_b32_e32 v42, v212, v43, vcc
	v_cmp_gt_i32_e32 vcc, s6, v120
	s_movk_i32 s6, 0x214
	s_nop 0
	v_cndmask_b32_e64 v43, 0, 1, vcc
	v_cmp_gt_i32_e32 vcc, s6, v120
	s_and_b64 s[18:19], s[48:49], vcc
	v_cndmask_b32_e64 v44, 0, 1, s[18:19]
	v_addc_co_u32_e64 v43, vcc, v44, v43, s[58:59]
	v_cmp_eq_u32_e32 vcc, 2, v43
	v_cmp_ne_u32_e64 s[54:55], 0, v43
	s_movk_i32 s6, 0x99
	v_cndmask_b32_e64 v44, 0, 1.0, vcc
	v_cmp_gt_u32_e32 vcc, 3, v43
	s_nop 1
	v_cndmask_b32_e32 v44, v214, v44, vcc
	v_cmp_lt_i32_e32 vcc, 18, v120
	v_fmac_f32_e32 v44, 0x3e38aa3b, v59
	s_and_b64 vcc, vcc, s[54:55]
	v_cndmask_b32_e32 v43, v212, v44, vcc
	v_cmp_gt_i32_e32 vcc, s6, v120
	s_movk_i32 s6, 0x219
	s_nop 0
	v_cndmask_b32_e64 v44, 0, 1, vcc
	v_cmp_gt_i32_e32 vcc, s6, v120
	s_and_b64 s[18:19], s[42:43], vcc
	v_cndmask_b32_e64 v45, 0, 1, s[18:19]
	v_addc_co_u32_e64 v44, vcc, v45, v44, s[60:61]
	v_cmp_eq_u32_e32 vcc, 2, v44
	v_cmp_ne_u32_e64 s[54:55], 0, v44
	s_movk_i32 s6, 0x9a
	v_cndmask_b32_e64 v45, 0, 1.0, vcc
	v_cmp_gt_u32_e32 vcc, 3, v44
	s_nop 1
	v_cndmask_b32_e32 v45, v214, v45, vcc
	v_cmp_lt_i32_e32 vcc, 23, v120
	v_fmac_f32_e32 v45, 0x3e38aa3b, v60
	s_and_b64 vcc, vcc, s[54:55]
	v_cndmask_b32_e32 v44, v212, v45, vcc
	v_cmp_gt_i32_e32 vcc, s6, v120
	s_movk_i32 s6, 0x21a
	s_nop 0
	v_cndmask_b32_e64 v45, 0, 1, vcc
	v_cmp_gt_i32_e32 vcc, s6, v120
	s_and_b64 s[18:19], s[44:45], vcc
	v_cndmask_b32_e64 v46, 0, 1, s[18:19]
	v_addc_co_u32_e64 v45, vcc, v46, v45, s[62:63]
	v_cmp_eq_u32_e32 vcc, 2, v45
	v_cmp_ne_u32_e64 s[54:55], 0, v45
	s_movk_i32 s6, 0x9b
	v_cndmask_b32_e64 v46, 0, 1.0, vcc
	v_cmp_gt_u32_e32 vcc, 3, v45
	s_nop 1
	v_cndmask_b32_e32 v46, v214, v46, vcc
	v_cmp_lt_i32_e32 vcc, 24, v120
	v_fmac_f32_e32 v46, 0x3e38aa3b, v61
	s_and_b64 vcc, vcc, s[54:55]
	v_cndmask_b32_e32 v45, v212, v46, vcc
	v_cmp_gt_i32_e32 vcc, s6, v120
	s_movk_i32 s6, 0x21b
	s_nop 0
	v_cndmask_b32_e64 v46, 0, 1, vcc
	v_cmp_gt_i32_e32 vcc, s6, v120
	s_and_b64 s[18:19], s[46:47], vcc
	v_cndmask_b32_e64 v47, 0, 1, s[18:19]
	v_addc_co_u32_e64 v46, vcc, v47, v46, s[64:65]
	v_cmp_eq_u32_e32 vcc, 2, v46
	v_cmp_ne_u32_e64 s[54:55], 0, v46
	s_movk_i32 s6, 0x9c
	v_cndmask_b32_e64 v47, 0, 1.0, vcc
	v_cmp_gt_u32_e32 vcc, 3, v46
	s_nop 1
	v_cndmask_b32_e32 v47, v214, v47, vcc
	v_cmp_lt_i32_e32 vcc, 25, v120
	v_fmac_f32_e32 v47, 0x3e38aa3b, v62
	s_and_b64 vcc, vcc, s[54:55]
	v_cndmask_b32_e32 v46, v212, v47, vcc
	v_cmp_gt_i32_e32 vcc, s6, v120
	s_movk_i32 s6, 0x21c
	s_nop 0
	v_cndmask_b32_e64 v47, 0, 1, vcc
	v_cmp_gt_i32_e32 vcc, s6, v120
	s_and_b64 s[18:19], s[48:49], vcc
	v_cndmask_b32_e64 v121, 0, 1, s[18:19]
	v_addc_co_u32_e64 v47, vcc, v121, v47, s[66:67]
	v_cmp_eq_u32_e32 vcc, 2, v47
	v_cmp_ne_u32_e64 s[54:55], 0, v47
	s_mov_b64 s[18:19], 0
	v_cndmask_b32_e64 v121, 0, 1.0, vcc
	v_cmp_gt_u32_e32 vcc, 3, v47
	s_nop 1
	v_cndmask_b32_e32 v121, v214, v121, vcc
	v_cmp_lt_i32_e32 vcc, 26, v120
	v_fmac_f32_e32 v121, 0x3e38aa3b, v63
	s_and_b64 vcc, vcc, s[54:55]
	v_cndmask_b32_e32 v47, v212, v121, vcc

.LBB0_791:
	s_add_i32 s16, s6, 0x60
	s_cmp_le_i32 s16, s18
	s_cselect_b64 s[16:17], -1, 0
	v_add_u32_e32 v32, s33, v97
	v_add_u32_e32 v33, s33, v88
	s_and_b64 s[16:17], s[16:17], s[14:15]
	s_andn2_b64 vcc, exec, s[16:17]
	v_add_u32_e32 v82, v32, v112
	v_add_u32_e32 v81, s6, v96
	v_add_u32_e32 v80, v33, v111
	ds_read_b128 v[218:221], v82
	ds_read_b128 v[222:225], v82 offset:32
	ds_read_b128 v[226:229], v82 offset:64
	ds_read_b128 v[230:233], v82 offset:96
	s_cbranch_vccnz .LBB0_793
	ds_read_b128 v[32:35], v82 offset:4608
	ds_read_b128 v[84:87], v82 offset:4640
	ds_read_b128 v[106:109], v82 offset:4672
	ds_read_b128 v[120:123], v82 offset:4704
	s_setprio 1
	s_waitcnt lgkmcnt(0)
	v_mfma_f32_32x32x16_bf16 v[32:47], v[32:35], v[64:67], 0
	v_mfma_f32_32x32x16_bf16 v[32:47], v[84:87], v[68:71], v[32:47]
	v_mfma_f32_32x32x16_bf16 v[32:47], v[106:109], v[72:75], v[32:47]
	v_mfma_f32_32x32x16_bf16 v[32:47], v[120:123], v[76:79], v[32:47]
	s_setprio 0
	s_nop 10
	v_add_u32_e32 v197, 0x2000, v80
	ds_read2_b64 v[180:183], v197 offset0:136 offset1:138
	ds_read2_b64 v[184:187], v197 offset0:140 offset1:142
	v_add_u32_e32 v197, 0x3000, v80
	ds_read2_b64 v[188:191], v197 offset0:168 offset1:170
	ds_read2_b64 v[192:195], v197 offset0:172 offset1:174
	v_mul_f32_e32 v60, 0x3e000000, v32
	v_mul_f32_e64 v61, |v60|, s37
	v_exp_f32_e32 v61, v61
	v_mul_f32_e32 v84, 0x3e000000, v33
	v_add_u32_e32 v62, 0x60, v81
	v_max_f32_e32 v60, 0, v60
	v_add_f32_e32 v61, 1.0, v61
	s_nop 1
	v_log_f32_e32 v61, v61
	s_nop 0
	v_mul_f32_e32 v85, 0x3f317217, v61
	v_fma_f32 v85, v61, s83, -v85
	v_fmac_f32_e32 v85, 0x3377d1cf, v61
	v_fmac_f32_e32 v85, 0x3f317217, v61
	s_nop 1
	v_mov_b32_e32 v61, v85
	v_mul_f32_e64 v83, |v84|, s37
	v_exp_f32_e32 v83, v83
	v_cmp_lt_i32_e32 vcc, v62, v102
	v_add_f32_e32 v61, v60, v61
	v_fma_f32 v32, v32, s81, -v61
	v_add_f32_e32 v62, 1.0, v83
	v_cndmask_b32_e64 v60, 0, -v61, vcc
	s_nop 0
	v_log_f32_e32 v62, v62
	s_nop 0
	v_cndmask_b32_e32 v83, v212, v32, vcc
	v_max_f32_e32 v32, 0, v84
	v_mul_f32_e32 v61, 0x3f317217, v62
	v_fma_f32 v61, v62, s83, -v61
	v_fmac_f32_e32 v61, 0x3377d1cf, v62
	v_fmac_f32_e32 v61, 0x3f317217, v62
	s_nop 1
	v_mul_f32_e32 v62, 0x3e000000, v34
	v_add_f32_e32 v61, v32, v61
	v_mul_f32_e64 v32, |v62|, s37
	v_exp_f32_e32 v84, v32
	v_add_u32_e32 v32, 0x61, v81
	v_cmp_lt_i32_e32 vcc, v32, v102
	v_fma_f32 v33, v33, s81, -v61
	v_add_f32_e32 v84, 1.0, v84
	v_cndmask_b32_e64 v32, 0, -v61, vcc
	s_nop 0
	v_log_f32_e32 v85, v84
	s_nop 0
	v_cndmask_b32_e32 v84, v212, v33, vcc
	v_max_f32_e32 v33, 0, v62
	v_mul_f32_e32 v61, 0x3f317217, v85
	v_fma_f32 v61, v85, s83, -v61
	v_fmac_f32_e32 v61, 0x3377d1cf, v85
	v_fmac_f32_e32 v61, 0x3f317217, v85
	s_nop 1
	v_add_f32_e32 v33, v33, v61
	v_mul_f32_e32 v61, 0x3e000000, v35
	v_mul_f32_e64 v62, |v61|, s37
	v_exp_f32_e32 v85, v62
	v_add_u32_e32 v62, 0x62, v81
	v_cmp_lt_i32_e32 vcc, v62, v102
	v_add_f32_e32 v85, 1.0, v85
	v_cndmask_b32_e64 v62, 0, -v33, vcc
	v_fma_f32 v33, v34, s81, -v33
	v_log_f32_e32 v85, v85
	s_nop 0
	v_cndmask_b32_e32 v86, v212, v33, vcc
	v_max_f32_e32 v33, 0, v61
	v_mul_f32_e32 v34, 0x3f317217, v85
	v_fma_f32 v34, v85, s83, -v34
	v_fmac_f32_e32 v34, 0x3377d1cf, v85
	v_fmac_f32_e32 v34, 0x3f317217, v85
	s_nop 1
	v_mul_f32_e32 v61, 0x3e000000, v36
	v_add_f32_e32 v33, v33, v34
	v_mul_f32_e64 v34, |v61|, s37
	v_exp_f32_e32 v85, v34
	v_add_u32_e32 v34, 0x63, v81
	v_cmp_lt_i32_e32 vcc, v34, v102
	v_add_f32_e32 v85, 1.0, v85
	v_cndmask_b32_e64 v34, 0, -v33, vcc
	v_fma_f32 v33, v35, s81, -v33
	v_log_f32_e32 v85, v85
	s_nop 0
	v_cndmask_b32_e32 v87, v212, v33, vcc
	v_max_f32_e32 v33, 0, v61
	v_mul_f32_e32 v35, 0x3f317217, v85
	v_fma_f32 v35, v85, s83, -v35
	v_fmac_f32_e32 v35, 0x3377d1cf, v85
	v_fmac_f32_e32 v35, 0x3f317217, v85
	s_nop 1
	v_add_f32_e32 v33, v33, v35
	v_mul_f32_e32 v35, 0x3e000000, v37
	v_mul_f32_e64 v61, |v35|, s37
	v_exp_f32_e32 v61, v61
	v_add_u32_e32 v85, 0x68, v81
	v_cmp_lt_i32_e32 vcc, v85, v102
	v_add_f32_e32 v61, 1.0, v61
	v_cndmask_b32_e64 v85, 0, -v33, vcc
	v_fma_f32 v33, v36, s81, -v33
	v_log_f32_e32 v61, v61
	s_nop 0
	v_cndmask_b32_e32 v99, v212, v33, vcc
	v_max_f32_e32 v33, 0, v35
	v_mul_f32_e32 v35, 0x3f317217, v61
	v_fma_f32 v35, v61, s83, -v35
	v_fmac_f32_e32 v35, 0x3377d1cf, v61
	v_fmac_f32_e32 v35, 0x3f317217, v61
	s_nop 1
	v_add_f32_e32 v33, v33, v35
	v_mul_f32_e32 v35, 0x3e000000, v38
	v_mul_f32_e64 v36, |v35|, s37
	v_exp_f32_e32 v36, v36
	v_add_u32_e32 v61, 0x69, v81
	v_cmp_lt_i32_e32 vcc, v61, v102
	v_add_f32_e32 v36, 1.0, v36
	v_cndmask_b32_e64 v103, 0, -v33, vcc
	v_fma_f32 v33, v37, s81, -v33
	v_log_f32_e32 v36, v36
	s_nop 0
	v_cndmask_b32_e32 v105, v212, v33, vcc
	v_max_f32_e32 v33, 0, v35
	v_add_u32_e32 v37, 0x6a, v81
	v_mul_f32_e32 v35, 0x3f317217, v36
	v_fma_f32 v35, v36, s83, -v35
	v_fmac_f32_e32 v35, 0x3377d1cf, v36
	v_fmac_f32_e32 v35, 0x3f317217, v36
	s_nop 1
	v_add_f32_e32 v33, v33, v35
	v_mul_f32_e32 v35, 0x3e000000, v39
	v_mul_f32_e64 v36, |v35|, s37
	v_exp_f32_e32 v36, v36
	v_cmp_lt_i32_e32 vcc, v37, v102
	v_add_f32_e32 v36, 1.0, v36
	v_cndmask_b32_e64 v106, 0, -v33, vcc
	v_fma_f32 v33, v38, s81, -v33
	v_log_f32_e32 v36, v36
	s_nop 0
	v_cndmask_b32_e32 v107, v212, v33, vcc
	v_max_f32_e32 v33, 0, v35
	v_add_u32_e32 v37, 0x6b, v81
	v_mul_f32_e32 v35, 0x3f317217, v36
	v_fma_f32 v35, v36, s83, -v35
	v_fmac_f32_e32 v35, 0x3377d1cf, v36
	v_fmac_f32_e32 v35, 0x3f317217, v36
	s_nop 1
	v_add_f32_e32 v33, v33, v35
	v_mul_f32_e32 v35, 0x3e000000, v40
	v_mul_f32_e64 v36, |v35|, s37
	v_exp_f32_e32 v36, v36
	v_cmp_lt_i32_e32 vcc, v37, v102
	v_add_f32_e32 v36, 1.0, v36
	v_cndmask_b32_e64 v108, 0, -v33, vcc
	v_fma_f32 v33, v39, s81, -v33
	v_log_f32_e32 v36, v36
	s_nop 0
	v_cndmask_b32_e32 v109, v212, v33, vcc
	v_max_f32_e32 v33, 0, v35
	v_add_u32_e32 v37, 0x70, v81
	v_mul_f32_e32 v35, 0x3f317217, v36
	v_fma_f32 v35, v36, s83, -v35
	v_fmac_f32_e32 v35, 0x3377d1cf, v36
	v_fmac_f32_e32 v35, 0x3f317217, v36
	v_add_u32_e32 v39, 0x71, v81
	s_nop 0
	v_add_f32_e32 v33, v33, v35
	v_mul_f32_e32 v35, 0x3e000000, v41
	v_mul_f32_e64 v36, |v35|, s37
	v_exp_f32_e32 v36, v36
	v_cmp_lt_i32_e32 vcc, v37, v102
	v_add_f32_e32 v36, 1.0, v36
	v_cndmask_b32_e64 v37, 0, -v33, vcc
	v_fma_f32 v33, v40, s81, -v33
	v_log_f32_e32 v36, v36
	s_nop 0
	v_cndmask_b32_e32 v38, v212, v33, vcc
	v_max_f32_e32 v33, 0, v35
	v_mul_f32_e32 v35, 0x3f317217, v36
	v_fma_f32 v35, v36, s83, -v35
	v_fmac_f32_e32 v35, 0x3377d1cf, v36
	v_fmac_f32_e32 v35, 0x3f317217, v36
	s_nop 1
	v_add_f32_e32 v33, v33, v35
	v_mul_f32_e32 v35, 0x3e000000, v42
	v_mul_f32_e64 v36, |v35|, s37
	v_exp_f32_e32 v36, v36
	v_cmp_lt_i32_e32 vcc, v39, v102
	v_add_f32_e32 v36, 1.0, v36
	v_cndmask_b32_e64 v39, 0, -v33, vcc
	v_fma_f32 v33, v41, s81, -v33
	v_log_f32_e32 v36, v36
	s_nop 0
	v_cndmask_b32_e32 v40, v212, v33, vcc
	v_max_f32_e32 v33, 0, v35
	v_add_u32_e32 v41, 0x72, v81
	v_mul_f32_e32 v35, 0x3f317217, v36
	v_fma_f32 v35, v36, s83, -v35
	v_fmac_f32_e32 v35, 0x3377d1cf, v36
	v_fmac_f32_e32 v35, 0x3f317217, v36
	v_add_f32_e32 v37, v37, v39
	s_nop 0
	v_add_f32_e32 v33, v33, v35
	v_mul_f32_e32 v35, 0x3e000000, v43
	v_mul_f32_e64 v36, |v35|, s37
	v_exp_f32_e32 v36, v36
	v_cmp_lt_i32_e32 vcc, v41, v102
	v_add_f32_e32 v36, 1.0, v36
	v_cndmask_b32_e64 v41, 0, -v33, vcc
	v_fma_f32 v33, v42, s81, -v33
	v_log_f32_e32 v36, v36
	s_nop 0
	v_cndmask_b32_e32 v42, v212, v33, vcc
	v_max_f32_e32 v33, 0, v35
	v_add_u32_e32 v61, 0x73, v81
	v_mul_f32_e32 v35, 0x3f317217, v36
	v_fma_f32 v35, v36, s83, -v35
	v_fmac_f32_e32 v35, 0x3377d1cf, v36
	v_fmac_f32_e32 v35, 0x3f317217, v36
	s_nop 1
	v_add_f32_e32 v33, v33, v35
	v_mul_f32_e32 v35, 0x3e000000, v44
	v_mul_f32_e64 v36, |v35|, s37
	v_exp_f32_e32 v36, v36
	v_cmp_lt_i32_e32 vcc, v61, v102
	v_add_f32_e32 v36, 1.0, v36
	v_cndmask_b32_e64 v120, 0, -v33, vcc
	v_fma_f32 v33, v43, s81, -v33
	v_log_f32_e32 v36, v36
	s_nop 0
	v_cndmask_b32_e32 v43, v212, v33, vcc
	v_max_f32_e32 v33, 0, v35
	v_add_u32_e32 v61, 0x78, v81
	v_mul_f32_e32 v35, 0x3f317217, v36
	v_fma_f32 v35, v36, s83, -v35
	v_fmac_f32_e32 v35, 0x3377d1cf, v36
	v_fmac_f32_e32 v35, 0x3f317217, v36
	s_nop 1
	v_add_f32_e32 v33, v33, v35
	v_mul_f32_e32 v35, 0x3e000000, v45
	v_mul_f32_e64 v36, |v35|, s37
	v_exp_f32_e32 v36, v36
	v_cmp_lt_i32_e32 vcc, v61, v102
	v_add_f32_e32 v36, 1.0, v36
	v_cndmask_b32_e64 v121, 0, -v33, vcc
	v_fma_f32 v33, v44, s81, -v33
	v_log_f32_e32 v36, v36
	s_nop 0
	v_cndmask_b32_e32 v44, v212, v33, vcc
	v_max_f32_e32 v33, 0, v35
	v_add_u32_e32 v61, 0x79, v81
	v_mul_f32_e32 v35, 0x3f317217, v36
	v_fma_f32 v35, v36, s83, -v35
	v_fmac_f32_e32 v35, 0x3377d1cf, v36
	v_fmac_f32_e32 v35, 0x3f317217, v36
	s_nop 1
	v_add_f32_e32 v33, v33, v35
	v_mul_f32_e32 v35, 0x3e000000, v46
	v_mul_f32_e64 v36, |v35|, s37
	v_exp_f32_e32 v36, v36
	v_cmp_lt_i32_e32 vcc, v61, v102
	v_add_f32_e32 v36, 1.0, v36
	v_cndmask_b32_e64 v122, 0, -v33, vcc
	v_fma_f32 v33, v45, s81, -v33
	v_log_f32_e32 v36, v36
	s_nop 0
	v_cndmask_b32_e32 v45, v212, v33, vcc
	v_max_f32_e32 v33, 0, v35
	v_add_u32_e32 v61, 0x7a, v81
	v_mul_f32_e32 v35, 0x3f317217, v36
	v_fma_f32 v35, v36, s83, -v35
	v_fmac_f32_e32 v35, 0x3377d1cf, v36
	v_fmac_f32_e32 v35, 0x3f317217, v36
	s_nop 1
	v_add_f32_e32 v33, v33, v35
	v_mul_f32_e32 v35, 0x3e000000, v47
	v_mul_f32_e64 v36, |v35|, s37
	v_exp_f32_e32 v36, v36
	v_cmp_lt_i32_e32 vcc, v61, v102
	v_add_f32_e32 v36, 1.0, v36
	v_cndmask_b32_e64 v123, 0, -v33, vcc
	v_fma_f32 v33, v46, s81, -v33
	v_log_f32_e32 v36, v36
	s_nop 0
	v_cndmask_b32_e32 v46, v212, v33, vcc
	v_max_f32_e32 v33, 0, v35
	v_mul_f32_e32 v35, 0x3f317217, v36
	v_fma_f32 v35, v36, s83, -v35
	v_fmac_f32_e32 v35, 0x3377d1cf, v36
	v_fmac_f32_e32 v35, 0x3f317217, v36
	s_nop 1
	v_add_f32_e32 v33, v33, v35
	v_add_u32_e32 v35, 0x7b, v81
	v_cmp_lt_i32_e32 vcc, v35, v102
	s_nop 1
	v_cndmask_b32_e64 v35, 0, -v33, vcc
	v_fma_f32 v33, v47, s81, -v33
	v_cndmask_b32_e32 v36, v212, v33, vcc
	v_add_f32_e32 v33, v85, v103
	v_add_f32_e32 v47, v106, v108
	v_add_f32_e32 v61, v33, v47
	v_add_f32_e32 v47, v121, v122
	v_add_f32_e32 v85, v123, v35
	v_add_f32_e32 v47, v47, v85
	ds_bpermute_b32 v85, v110, v47
	v_add_f32_e32 v121, v41, v120
	v_add_f32_e32 v37, v37, v121
	ds_bpermute_b32 v121, v110, v37
	ds_bpermute_b32 v33, v110, v61
	s_waitcnt lgkmcnt(0)
	v_cndmask_b32_e64 v124, 0, v85, s[52:53]
	v_add_f32_e32 v124, v63, v124
	v_add_f32_e32 v36, v124, v36
	v_mul_f32_e32 v36, 0x3fb8aa3b, v36
	v_add_f32_e32 v35, v124, v35
	v_exp_f32_e32 v125, v36
	v_add_f32_e32 v36, v46, v35
	v_mul_f32_e32 v36, 0x3fb8aa3b, v36
	v_add_f32_e32 v35, v123, v35
	v_exp_f32_e32 v124, v36
	v_add_f32_e32 v36, v45, v35
	v_add_f32_e32 v35, v122, v35
	v_add_f32_e32 v35, v44, v35
	v_mul_f32_e32 v35, 0x3fb8aa3b, v35
	v_mul_f32_e32 v36, 0x3fb8aa3b, v36
	v_exp_f32_e32 v122, v35
	v_add_f32_e32 v35, v47, v85
	v_exp_f32_e32 v46, v36
	v_add_f32_e32 v35, v63, v35
	v_cndmask_b32_e64 v36, 0, v121, s[52:53]
	v_add_f32_e32 v36, v36, v35
	v_add_f32_e32 v43, v43, v36
	v_add_f32_e32 v36, v120, v36
	v_add_f32_e32 v42, v42, v36
	v_add_f32_e32 v36, v41, v36
	v_add_f32_e32 v40, v40, v36
	v_add_f32_e32 v36, v39, v36
	v_add_f32_e32 v36, v38, v36
	v_mul_f32_e32 v36, 0x3fb8aa3b, v36
	v_add_f32_e32 v63, v37, v121
	v_exp_f32_e32 v85, v36
	v_pk_add_f32 v[36:37], v[62:63], v[34:35]
	v_pk_add_f32 v[38:39], v[60:61], v[32:33]
	v_mul_f32_e32 v40, 0x3fb8aa3b, v40
	v_pk_add_f32 v[38:39], v[38:39], v[36:37]
	v_exp_f32_e32 v44, v40
	v_cndmask_b32_e64 v40, 0, v33, s[52:53]
	ds_bpermute_b32 v33, v110, v38
	v_add_f32_e32 v35, v40, v37
	v_add_f32_e32 v36, v109, v35
	v_add_f32_e32 v35, v108, v35
	v_mul_f32_e32 v42, 0x3fb8aa3b, v42
	s_waitcnt lgkmcnt(0)
	v_cndmask_b32_e64 v41, 0, v33, s[52:53]
	v_add_f32_e32 v41, v41, v39
	v_add_f32_e32 v37, v107, v35
	v_add_f32_e32 v35, v106, v35
	v_add_f32_e32 v34, v34, v41
	v_exp_f32_e32 v47, v42
	v_add_f32_e32 v40, v105, v35
	v_add_f32_e32 v35, v103, v35
	v_add_f32_e32 v42, v87, v41
	v_add_f32_e32 v41, v86, v34
	v_add_f32_e32 v34, v62, v34
	v_mul_f32_e32 v43, 0x3fb8aa3b, v43
	v_add_f32_e32 v35, v99, v35
	v_add_f32_e32 v32, v32, v34
	v_exp_f32_e32 v45, v43
	v_mul_f32_e32 v40, 0x3fb8aa3b, v40
	v_mul_f32_e32 v35, 0x3fb8aa3b, v35
	v_mul_f32_e32 v42, 0x3fb8aa3b, v42
	v_mul_f32_e32 v41, 0x3fb8aa3b, v41
	v_add_f32_e32 v43, v84, v34
	v_add_f32_e32 v32, v83, v32
	v_mul_f32_e32 v36, 0x3fb8aa3b, v36
	v_mul_f32_e32 v37, 0x3fb8aa3b, v37
	v_exp_f32_e32 v40, v40
	v_exp_f32_e32 v35, v35
	v_exp_f32_e32 v42, v42
	v_mul_f32_e32 v43, 0x3fb8aa3b, v43
	v_mul_f32_e32 v32, 0x3fb8aa3b, v32
	v_exp_f32_e32 v34, v41
	v_exp_f32_e32 v36, v36
	v_exp_f32_e32 v37, v37
	v_exp_f32_e32 v43, v43
	v_exp_f32_e32 v32, v32
	v_add_f32_e32 v33, v38, v33
	v_add_f32_e32 v63, v33, v39
	v_cvt_pk_bf16_f32 v33, v34, v42
	v_cvt_pk_bf16_f32 v34, v35, v40
	v_cvt_pk_bf16_f32 v32, v32, v43
	v_cvt_pk_bf16_f32 v35, v37, v36
	v_cvt_pk_bf16_f32 v44, v85, v44
	v_cvt_pk_bf16_f32 v45, v47, v45
	v_cvt_pk_bf16_f32 v46, v122, v46
	v_cvt_pk_bf16_f32 v47, v124, v125
	s_setprio 1
	s_waitcnt lgkmcnt(0)
	v_mfma_f32_32x32x16_bf16 v[16:31], v[180:183], v[32:35], v[16:31]
	v_mfma_f32_32x32x16_bf16 v[16:31], v[184:187], v[44:47], v[16:31]
	s_setprio 0
	s_setprio 1
	s_waitcnt lgkmcnt(0)
	v_mfma_f32_32x32x16_bf16 v[0:15], v[188:191], v[32:35], v[0:15]
	v_mfma_f32_32x32x16_bf16 v[0:15], v[192:195], v[44:47], v[0:15]
	s_setprio 0
	v_cmp_gt_f32_e32 vcc, s5, v63
	s_cmp_lg_u64 vcc, exec
	s_cselect_b64 s[14:15], -1, 0
.LBB0_793:
	s_add_i32 s16, s6, 64
	s_cmp_le_i32 s16, s18
	s_cselect_b64 s[16:17], -1, 0
	s_and_b64 s[16:17], s[16:17], s[14:15]
	s_andn2_b64 vcc, exec, s[16:17]
	s_cbranch_vccnz .LBB0_795
	s_setprio 1
	s_waitcnt lgkmcnt(0)
	v_mfma_f32_32x32x16_bf16 v[32:47], v[218:221], v[64:67], 0
	v_mfma_f32_32x32x16_bf16 v[32:47], v[222:225], v[68:71], v[32:47]
	v_mfma_f32_32x32x16_bf16 v[32:47], v[226:229], v[72:75], v[32:47]
	v_mfma_f32_32x32x16_bf16 v[32:47], v[230:233], v[76:79], v[32:47]
	s_setprio 0
	s_nop 10
	v_add_u32_e32 v197, 0x2000, v80
	ds_read2_b64 v[180:183], v197 offset0:128 offset1:130
	ds_read2_b64 v[184:187], v197 offset0:132 offset1:134
	v_add_u32_e32 v197, 0x3000, v80
	ds_read2_b64 v[188:191], v197 offset0:160 offset1:162
	ds_read2_b64 v[192:195], v197 offset0:164 offset1:166
	v_mul_f32_e32 v60, 0x3e000000, v32
	v_mul_f32_e64 v61, |v60|, s37
	v_exp_f32_e32 v61, v61
	v_mul_f32_e32 v83, 0x3e000000, v33
	v_add_u32_e32 v62, 64, v81
	v_max_f32_e32 v60, 0, v60
	v_add_f32_e32 v61, 1.0, v61
	s_nop 1
	v_log_f32_e32 v61, v61
	s_nop 0
	v_mul_f32_e32 v84, 0x3f317217, v61
	v_fma_f32 v84, v61, s83, -v84
	v_fmac_f32_e32 v84, 0x3377d1cf, v61
	v_fmac_f32_e32 v84, 0x3f317217, v61
	s_nop 1
	v_mov_b32_e32 v61, v84
	v_mul_f32_e64 v82, |v83|, s37
	v_exp_f32_e32 v82, v82
	v_cmp_lt_i32_e32 vcc, v62, v102
	v_add_f32_e32 v61, v60, v61
	v_fma_f32 v32, v32, s81, -v61
	v_add_f32_e32 v62, 1.0, v82
	v_cndmask_b32_e64 v60, 0, -v61, vcc
	s_nop 0
	v_log_f32_e32 v62, v62
	s_nop 0
	v_cndmask_b32_e32 v82, v212, v32, vcc
	v_max_f32_e32 v32, 0, v83
	v_mul_f32_e32 v61, 0x3f317217, v62
	v_fma_f32 v61, v62, s83, -v61
	v_fmac_f32_e32 v61, 0x3377d1cf, v62
	v_fmac_f32_e32 v61, 0x3f317217, v62
	s_nop 1
	v_mul_f32_e32 v62, 0x3e000000, v34
	v_add_f32_e32 v61, v32, v61
	v_mul_f32_e64 v32, |v62|, s37
	v_exp_f32_e32 v83, v32
	v_add_u32_e32 v32, 0x41, v81
	v_cmp_lt_i32_e32 vcc, v32, v102
	v_fma_f32 v33, v33, s81, -v61
	v_add_f32_e32 v83, 1.0, v83
	v_cndmask_b32_e64 v32, 0, -v61, vcc
	s_nop 0
	v_log_f32_e32 v84, v83
	s_nop 0
	v_cndmask_b32_e32 v83, v212, v33, vcc
	v_max_f32_e32 v33, 0, v62
	v_mul_f32_e32 v61, 0x3f317217, v84
	v_fma_f32 v61, v84, s83, -v61
	v_fmac_f32_e32 v61, 0x3377d1cf, v84
	v_fmac_f32_e32 v61, 0x3f317217, v84
	s_nop 1
	v_add_f32_e32 v33, v33, v61
	v_mul_f32_e32 v61, 0x3e000000, v35
	v_mul_f32_e64 v62, |v61|, s37
	v_exp_f32_e32 v84, v62
	v_add_u32_e32 v62, 0x42, v81
	v_cmp_lt_i32_e32 vcc, v62, v102
	v_add_f32_e32 v84, 1.0, v84
	v_cndmask_b32_e64 v62, 0, -v33, vcc
	v_fma_f32 v33, v34, s81, -v33
	v_log_f32_e32 v84, v84
	s_nop 0
	v_cndmask_b32_e32 v85, v212, v33, vcc
	v_max_f32_e32 v33, 0, v61
	v_mul_f32_e32 v34, 0x3f317217, v84
	v_fma_f32 v34, v84, s83, -v34
	v_fmac_f32_e32 v34, 0x3377d1cf, v84
	v_fmac_f32_e32 v34, 0x3f317217, v84
	s_nop 1
	v_mul_f32_e32 v61, 0x3e000000, v36
	v_add_f32_e32 v33, v33, v34
	v_mul_f32_e64 v34, |v61|, s37
	v_exp_f32_e32 v84, v34
	v_add_u32_e32 v34, 0x43, v81
	v_cmp_lt_i32_e32 vcc, v34, v102
	v_add_f32_e32 v84, 1.0, v84
	v_cndmask_b32_e64 v34, 0, -v33, vcc
	v_fma_f32 v33, v35, s81, -v33
	v_log_f32_e32 v84, v84
	s_nop 0
	v_cndmask_b32_e32 v86, v212, v33, vcc
	v_max_f32_e32 v33, 0, v61
	v_mul_f32_e32 v35, 0x3f317217, v84
	v_fma_f32 v35, v84, s83, -v35
	v_fmac_f32_e32 v35, 0x3377d1cf, v84
	v_fmac_f32_e32 v35, 0x3f317217, v84
	s_nop 1
	v_add_f32_e32 v33, v33, v35
	v_mul_f32_e32 v35, 0x3e000000, v37
	v_mul_f32_e64 v61, |v35|, s37
	v_exp_f32_e32 v61, v61
	v_add_u32_e32 v84, 0x48, v81
	v_cmp_lt_i32_e32 vcc, v84, v102
	v_add_f32_e32 v61, 1.0, v61
	v_cndmask_b32_e64 v84, 0, -v33, vcc
	v_fma_f32 v33, v36, s81, -v33
	v_log_f32_e32 v61, v61
	s_nop 0
	v_cndmask_b32_e32 v87, v212, v33, vcc
	v_max_f32_e32 v33, 0, v35
	v_mul_f32_e32 v35, 0x3f317217, v61
	v_fma_f32 v35, v61, s83, -v35
	v_fmac_f32_e32 v35, 0x3377d1cf, v61
	v_fmac_f32_e32 v35, 0x3f317217, v61
	s_nop 1
	v_add_f32_e32 v33, v33, v35
	v_mul_f32_e32 v35, 0x3e000000, v38
	v_mul_f32_e64 v36, |v35|, s37
	v_exp_f32_e32 v36, v36
	v_add_u32_e32 v61, 0x49, v81
	v_cmp_lt_i32_e32 vcc, v61, v102
	v_add_f32_e32 v36, 1.0, v36
	v_cndmask_b32_e64 v99, 0, -v33, vcc
	v_fma_f32 v33, v37, s81, -v33
	v_log_f32_e32 v36, v36
	s_nop 0
	v_cndmask_b32_e32 v103, v212, v33, vcc
	v_max_f32_e32 v33, 0, v35
	v_add_u32_e32 v37, 0x4a, v81
	v_mul_f32_e32 v35, 0x3f317217, v36
	v_fma_f32 v35, v36, s83, -v35
	v_fmac_f32_e32 v35, 0x3377d1cf, v36
	v_fmac_f32_e32 v35, 0x3f317217, v36
	s_nop 1
	v_add_f32_e32 v33, v33, v35
	v_mul_f32_e32 v35, 0x3e000000, v39
	v_mul_f32_e64 v36, |v35|, s37
	v_exp_f32_e32 v36, v36
	v_cmp_lt_i32_e32 vcc, v37, v102
	v_add_f32_e32 v36, 1.0, v36
	v_cndmask_b32_e64 v105, 0, -v33, vcc
	v_fma_f32 v33, v38, s81, -v33
	v_log_f32_e32 v36, v36
	s_nop 0
	v_cndmask_b32_e32 v106, v212, v33, vcc
	v_max_f32_e32 v33, 0, v35
	v_add_u32_e32 v37, 0x4b, v81
	v_mul_f32_e32 v35, 0x3f317217, v36
	v_fma_f32 v35, v36, s83, -v35
	v_fmac_f32_e32 v35, 0x3377d1cf, v36
	v_fmac_f32_e32 v35, 0x3f317217, v36
	s_nop 1
	v_add_f32_e32 v33, v33, v35
	v_mul_f32_e32 v35, 0x3e000000, v40
	v_mul_f32_e64 v36, |v35|, s37
	v_exp_f32_e32 v36, v36
	v_cmp_lt_i32_e32 vcc, v37, v102
	v_add_f32_e32 v36, 1.0, v36
	v_cndmask_b32_e64 v107, 0, -v33, vcc
	v_fma_f32 v33, v39, s81, -v33
	v_log_f32_e32 v36, v36
	s_nop 0
	v_cndmask_b32_e32 v108, v212, v33, vcc
	v_max_f32_e32 v33, 0, v35
	v_add_u32_e32 v37, 0x50, v81
	v_mul_f32_e32 v35, 0x3f317217, v36
	v_fma_f32 v35, v36, s83, -v35
	v_fmac_f32_e32 v35, 0x3377d1cf, v36
	v_fmac_f32_e32 v35, 0x3f317217, v36
	v_add_u32_e32 v39, 0x51, v81
	s_nop 0
	v_add_f32_e32 v33, v33, v35
	v_mul_f32_e32 v35, 0x3e000000, v41
	v_mul_f32_e64 v36, |v35|, s37
	v_exp_f32_e32 v36, v36
	v_cmp_lt_i32_e32 vcc, v37, v102
	v_add_f32_e32 v36, 1.0, v36
	v_cndmask_b32_e64 v37, 0, -v33, vcc
	v_fma_f32 v33, v40, s81, -v33
	v_log_f32_e32 v36, v36
	s_nop 0
	v_cndmask_b32_e32 v38, v212, v33, vcc
	v_max_f32_e32 v33, 0, v35
	v_mul_f32_e32 v35, 0x3f317217, v36
	v_fma_f32 v35, v36, s83, -v35
	v_fmac_f32_e32 v35, 0x3377d1cf, v36
	v_fmac_f32_e32 v35, 0x3f317217, v36
	s_nop 1
	v_add_f32_e32 v33, v33, v35
	v_mul_f32_e32 v35, 0x3e000000, v42
	v_mul_f32_e64 v36, |v35|, s37
	v_exp_f32_e32 v36, v36
	v_cmp_lt_i32_e32 vcc, v39, v102
	v_add_f32_e32 v36, 1.0, v36
	v_cndmask_b32_e64 v39, 0, -v33, vcc
	v_fma_f32 v33, v41, s81, -v33
	v_log_f32_e32 v36, v36
	s_nop 0
	v_cndmask_b32_e32 v40, v212, v33, vcc
	v_max_f32_e32 v33, 0, v35
	v_add_u32_e32 v41, 0x52, v81
	v_mul_f32_e32 v35, 0x3f317217, v36
	v_fma_f32 v35, v36, s83, -v35
	v_fmac_f32_e32 v35, 0x3377d1cf, v36
	v_fmac_f32_e32 v35, 0x3f317217, v36
	v_add_f32_e32 v37, v37, v39
	s_nop 0
	v_add_f32_e32 v33, v33, v35
	v_mul_f32_e32 v35, 0x3e000000, v43
	v_mul_f32_e64 v36, |v35|, s37
	v_exp_f32_e32 v36, v36
	v_cmp_lt_i32_e32 vcc, v41, v102
	v_add_f32_e32 v36, 1.0, v36
	v_cndmask_b32_e64 v41, 0, -v33, vcc
	v_fma_f32 v33, v42, s81, -v33
	v_log_f32_e32 v36, v36
	s_nop 0
	v_cndmask_b32_e32 v42, v212, v33, vcc
	v_max_f32_e32 v33, 0, v35
	v_add_u32_e32 v61, 0x53, v81
	v_mul_f32_e32 v35, 0x3f317217, v36
	v_fma_f32 v35, v36, s83, -v35
	v_fmac_f32_e32 v35, 0x3377d1cf, v36
	v_fmac_f32_e32 v35, 0x3f317217, v36
	s_nop 1
	v_add_f32_e32 v33, v33, v35
	v_mul_f32_e32 v35, 0x3e000000, v44
	v_mul_f32_e64 v36, |v35|, s37
	v_exp_f32_e32 v36, v36
	v_cmp_lt_i32_e32 vcc, v61, v102
	v_add_f32_e32 v36, 1.0, v36
	v_cndmask_b32_e64 v109, 0, -v33, vcc
	v_fma_f32 v33, v43, s81, -v33
	v_log_f32_e32 v36, v36
	s_nop 0
	v_cndmask_b32_e32 v43, v212, v33, vcc
	v_max_f32_e32 v33, 0, v35
	v_add_u32_e32 v61, 0x58, v81
	v_mul_f32_e32 v35, 0x3f317217, v36
	v_fma_f32 v35, v36, s83, -v35
	v_fmac_f32_e32 v35, 0x3377d1cf, v36
	v_fmac_f32_e32 v35, 0x3f317217, v36
	s_nop 1
	v_add_f32_e32 v33, v33, v35
	v_mul_f32_e32 v35, 0x3e000000, v45
	v_mul_f32_e64 v36, |v35|, s37
	v_exp_f32_e32 v36, v36
	v_cmp_lt_i32_e32 vcc, v61, v102
	v_add_f32_e32 v36, 1.0, v36
	v_cndmask_b32_e64 v120, 0, -v33, vcc
	v_fma_f32 v33, v44, s81, -v33
	v_log_f32_e32 v36, v36
	s_nop 0
	v_cndmask_b32_e32 v44, v212, v33, vcc
	v_max_f32_e32 v33, 0, v35
	v_add_u32_e32 v61, 0x59, v81
	v_mul_f32_e32 v35, 0x3f317217, v36
	v_fma_f32 v35, v36, s83, -v35
	v_fmac_f32_e32 v35, 0x3377d1cf, v36
	v_fmac_f32_e32 v35, 0x3f317217, v36
	s_nop 1
	v_add_f32_e32 v33, v33, v35
	v_mul_f32_e32 v35, 0x3e000000, v46
	v_mul_f32_e64 v36, |v35|, s37
	v_exp_f32_e32 v36, v36
	v_cmp_lt_i32_e32 vcc, v61, v102
	v_add_f32_e32 v36, 1.0, v36
	v_cndmask_b32_e64 v121, 0, -v33, vcc
	v_fma_f32 v33, v45, s81, -v33
	v_log_f32_e32 v36, v36
	s_nop 0
	v_cndmask_b32_e32 v45, v212, v33, vcc
	v_max_f32_e32 v33, 0, v35
	v_add_u32_e32 v61, 0x5a, v81
	v_mul_f32_e32 v35, 0x3f317217, v36
	v_fma_f32 v35, v36, s83, -v35
	v_fmac_f32_e32 v35, 0x3377d1cf, v36
	v_fmac_f32_e32 v35, 0x3f317217, v36
	s_nop 1
	v_add_f32_e32 v33, v33, v35
	v_mul_f32_e32 v35, 0x3e000000, v47
	v_mul_f32_e64 v36, |v35|, s37
	v_exp_f32_e32 v36, v36
	v_cmp_lt_i32_e32 vcc, v61, v102
	v_add_f32_e32 v36, 1.0, v36
	v_cndmask_b32_e64 v122, 0, -v33, vcc
	v_fma_f32 v33, v46, s81, -v33
	v_log_f32_e32 v36, v36
	s_nop 0
	v_cndmask_b32_e32 v46, v212, v33, vcc
	v_max_f32_e32 v33, 0, v35
	v_mul_f32_e32 v35, 0x3f317217, v36
	v_fma_f32 v35, v36, s83, -v35
	v_fmac_f32_e32 v35, 0x3377d1cf, v36
	v_fmac_f32_e32 v35, 0x3f317217, v36
	s_nop 1
	v_add_f32_e32 v33, v33, v35
	v_add_u32_e32 v35, 0x5b, v81
	v_cmp_lt_i32_e32 vcc, v35, v102
	s_nop 1
	v_cndmask_b32_e64 v35, 0, -v33, vcc
	v_fma_f32 v33, v47, s81, -v33
	v_cndmask_b32_e32 v36, v212, v33, vcc
	v_add_f32_e32 v33, v84, v99
	v_add_f32_e32 v47, v105, v107
	v_add_f32_e32 v61, v33, v47
	v_add_f32_e32 v47, v120, v121
	v_add_f32_e32 v81, v122, v35
	v_add_f32_e32 v47, v47, v81
	ds_bpermute_b32 v81, v110, v47
	v_add_f32_e32 v84, v41, v109
	v_add_f32_e32 v37, v37, v84
	ds_bpermute_b32 v84, v110, v37
	ds_bpermute_b32 v33, v110, v61
	s_waitcnt lgkmcnt(0)
	v_cndmask_b32_e64 v120, 0, v81, s[52:53]
	v_add_f32_e32 v120, v63, v120
	v_add_f32_e32 v36, v120, v36
	v_mul_f32_e32 v36, 0x3fb8aa3b, v36
	v_add_f32_e32 v35, v120, v35
	v_exp_f32_e32 v123, v36
	v_add_f32_e32 v36, v46, v35
	v_mul_f32_e32 v36, 0x3fb8aa3b, v36
	v_add_f32_e32 v35, v122, v35
	v_exp_f32_e32 v120, v36
	v_add_f32_e32 v36, v45, v35
	v_add_f32_e32 v35, v121, v35
	v_add_f32_e32 v35, v44, v35
	v_mul_f32_e32 v35, 0x3fb8aa3b, v35
	v_mul_f32_e32 v36, 0x3fb8aa3b, v36
	v_exp_f32_e32 v121, v35
	v_add_f32_e32 v35, v47, v81
	v_exp_f32_e32 v46, v36
	v_add_f32_e32 v35, v63, v35
	v_cndmask_b32_e64 v36, 0, v84, s[52:53]
	v_add_f32_e32 v36, v36, v35
	v_add_f32_e32 v43, v43, v36
	v_add_f32_e32 v36, v109, v36
	v_add_f32_e32 v42, v42, v36
	v_add_f32_e32 v36, v41, v36
	v_add_f32_e32 v40, v40, v36
	v_add_f32_e32 v36, v39, v36
	v_add_f32_e32 v36, v38, v36
	v_mul_f32_e32 v36, 0x3fb8aa3b, v36
	v_add_f32_e32 v63, v37, v84
	v_exp_f32_e32 v81, v36
	v_pk_add_f32 v[36:37], v[62:63], v[34:35]
	v_pk_add_f32 v[38:39], v[60:61], v[32:33]
	v_mul_f32_e32 v40, 0x3fb8aa3b, v40
	v_pk_add_f32 v[38:39], v[38:39], v[36:37]
	v_exp_f32_e32 v44, v40
	v_cndmask_b32_e64 v40, 0, v33, s[52:53]
	ds_bpermute_b32 v33, v110, v38
	v_add_f32_e32 v35, v40, v37
	v_add_f32_e32 v36, v108, v35
	v_add_f32_e32 v35, v107, v35
	v_mul_f32_e32 v42, 0x3fb8aa3b, v42
	s_waitcnt lgkmcnt(0)
	v_cndmask_b32_e64 v41, 0, v33, s[52:53]
	v_add_f32_e32 v41, v41, v39
	v_add_f32_e32 v37, v106, v35
	v_add_f32_e32 v35, v105, v35
	v_add_f32_e32 v34, v34, v41
	v_exp_f32_e32 v47, v42
	v_add_f32_e32 v40, v103, v35
	v_add_f32_e32 v35, v99, v35
	v_add_f32_e32 v42, v86, v41
	v_add_f32_e32 v41, v85, v34
	v_add_f32_e32 v34, v62, v34
	v_mul_f32_e32 v43, 0x3fb8aa3b, v43
	v_add_f32_e32 v35, v87, v35
	v_add_f32_e32 v32, v32, v34
	v_exp_f32_e32 v45, v43
	v_mul_f32_e32 v40, 0x3fb8aa3b, v40
	v_mul_f32_e32 v35, 0x3fb8aa3b, v35
	v_mul_f32_e32 v42, 0x3fb8aa3b, v42
	v_mul_f32_e32 v41, 0x3fb8aa3b, v41
	v_add_f32_e32 v43, v83, v34
	v_add_f32_e32 v32, v82, v32
	v_mul_f32_e32 v36, 0x3fb8aa3b, v36
	v_mul_f32_e32 v37, 0x3fb8aa3b, v37
	v_exp_f32_e32 v40, v40
	v_exp_f32_e32 v35, v35
	v_exp_f32_e32 v42, v42
	v_mul_f32_e32 v43, 0x3fb8aa3b, v43
	v_mul_f32_e32 v32, 0x3fb8aa3b, v32
	v_exp_f32_e32 v34, v41
	v_exp_f32_e32 v36, v36
	v_exp_f32_e32 v37, v37
	v_exp_f32_e32 v43, v43
	v_exp_f32_e32 v32, v32
	v_add_f32_e32 v33, v38, v33
	v_add_f32_e32 v63, v33, v39
	v_cvt_pk_bf16_f32 v33, v34, v42
	v_cvt_pk_bf16_f32 v34, v35, v40
	v_cvt_pk_bf16_f32 v32, v32, v43
	v_cvt_pk_bf16_f32 v35, v37, v36
	v_cvt_pk_bf16_f32 v44, v81, v44
	v_cvt_pk_bf16_f32 v45, v47, v45
	v_cvt_pk_bf16_f32 v46, v121, v46
	v_cvt_pk_bf16_f32 v47, v120, v123
	s_setprio 1
	s_waitcnt lgkmcnt(0)
	v_mfma_f32_32x32x16_bf16 v[16:31], v[180:183], v[32:35], v[16:31]
	v_mfma_f32_32x32x16_bf16 v[16:31], v[184:187], v[44:47], v[16:31]
	s_setprio 0
	s_setprio 1
	s_waitcnt lgkmcnt(0)
	v_mfma_f32_32x32x16_bf16 v[0:15], v[188:191], v[32:35], v[0:15]
	v_mfma_f32_32x32x16_bf16 v[0:15], v[192:195], v[44:47], v[0:15]
	s_setprio 0
	v_cmp_gt_f32_e32 vcc, s5, v63
	s_cmp_lg_u64 vcc, exec
	s_cselect_b64 s[14:15], -1, 0
